# HGRN2 scan step: intra-chunk score MFMA operands read 4 k-steps deep with counted lgkmcnt instead of read-wait-mfma (v010 base)
# baseline (speedup 1.0000x reference)
; #define MFMA32(a, b, c) __builtin_amdgcn_mfma_f32_32x32x16_bf16((a), (b), (c), 0, 0, 0)
; DI int v_st(int k, int c) { const int kk = (k & ~0xC) | ((k & 4) << 1) | ((k & 8) >> 1); return ((kk >> 3) * 4 + (c >> 5)) * 512 + ((kk & 7) * 32 + (c & 31)) * 2; }
; template <int VAR> DI void scan_item(int b, int h, int dir, const u16* __restrict__ KKb, const u16* __restrict__ RI, const u16* __restrict__ RQ, u16* __restrict__ OUT, char* lds) {
;     ...
;       *(s16x8*)(lds + SC_VV + v_st(sr, sc)) = cv0; *(s16x8*)(lds + SC_VV + v_st(32 + sr, sc)) = cv1; }
;     __syncthreads();
;     if (VAR != 1 && VAR != 3) {
;     if (!isctx) {
;       f32x16 p0 = {}, p1 = {};
;       const int trow = tb * 32 + r32;
; #pragma unroll
;       for (int ks = 0; ks < 8; ++ks) { const int cb = (ks * 16 + hi * 8) * 2;
;         const s16x8 qf = *(const s16x8*)(lds + SC_QP + KSWZ(trow, cb));
;         const s16x8 kf0 = *(const s16x8*)(lds + SC_KP + KSWZ(r32, cb));
;         p0 = MFMA32(kf0, qf, p0);
;         if (tb == 1) { const s16x8 kf1 = *(const s16x8*)(lds + SC_KP + KSWZ(32 + r32, cb)); p1 = MFMA32(kf1, qf, p1); } }
.LBB0_342:
	s_and_b64 vcc, exec, s[28:29]
	ds_write_b128 v171, v[32:35]
	ds_write_b128 v172, v[36:39]
	s_waitcnt lgkmcnt(0)
	s_barrier
	s_cbranch_vccz .LBB0_273
	v_add_u32_e32 v76, v125, v135
	v_add_u32_e32 v78, v125, v136
	v_add_u32_e32 v79, v125, v137
	v_add_u32_e32 v80, v125, v138
	v_add_u32_e32 v81, v125, v139
	v_add_u32_e32 v82, v125, v140
	v_add_u32_e32 v83, v125, v141
	v_add_u32_e32 v84, v125, v142
	s_mov_b32 s61, s60
	s_mov_b32 s62, s60
	s_mov_b32 s63, s60
	s_mov_b32 s64, s60
	s_mov_b32 s65, s60
	s_mov_b32 s66, s60
	s_mov_b32 s67, s60
	s_mov_b32 s68, s60
	s_mov_b32 s69, s60
	s_mov_b32 s70, s60
	s_mov_b32 s71, s60
	s_mov_b32 s72, s60
	s_mov_b32 s73, s60
	s_mov_b32 s74, s60
	s_mov_b32 s75, s60
	v_mov_b64_e32 v[48:49], s[60:61]
	v_mov_b64_e32 v[50:51], s[62:63]
	v_mov_b64_e32 v[52:53], s[64:65]
	v_mov_b64_e32 v[54:55], s[66:67]
	v_mov_b64_e32 v[56:57], s[68:69]
	v_mov_b64_e32 v[58:59], s[70:71]
	v_mov_b64_e32 v[60:61], s[72:73]
	v_mov_b64_e32 v[62:63], s[74:75]
	s_and_b64 vcc, exec, s[80:81]
	s_cbranch_vccz .Lscan_qk_tb0
	v_add_u32_e32 v85, v126, v135
	ds_read_b128 v[204:207], v76
	ds_read_b128 v[208:211], v85 offset:16384
	ds_read_b128 v[212:215], v85 offset:24576
	v_add_u32_e32 v202, v126, v136
	ds_read_b128 v[216:219], v78
	ds_read_b128 v[220:223], v202 offset:16384
	ds_read_b128 v[224:227], v202 offset:24576
	v_add_u32_e32 v203, v126, v137
	ds_read_b128 v[228:231], v79
	ds_read_b128 v[232:235], v203 offset:16384
	ds_read_b128 v[236:239], v203 offset:24576
	v_add_u32_e32 v244, v126, v138
	ds_read_b128 v[240:243], v80
	ds_read_b128 v[72:75], v244 offset:16384
	ds_read_b128 v[86:89], v244 offset:24576
	s_waitcnt lgkmcnt(10)
	v_mfma_f32_32x32x16_bf16 v[32:47], v[208:211], v[204:207], 0
	s_waitcnt lgkmcnt(9)
	v_mfma_f32_32x32x16_bf16 v[48:63], v[212:215], v[204:207], 0
	v_add_u32_e32 v85, v126, v139
	ds_read_b128 v[204:207], v81
	ds_read_b128 v[208:211], v85 offset:16384
	ds_read_b128 v[212:215], v85 offset:24576
	s_waitcnt lgkmcnt(10)
	v_mfma_f32_32x32x16_bf16 v[32:47], v[220:223], v[216:219], v[32:47]
	s_waitcnt lgkmcnt(9)
	v_mfma_f32_32x32x16_bf16 v[48:63], v[224:227], v[216:219], v[48:63]
	v_add_u32_e32 v202, v126, v140
	ds_read_b128 v[216:219], v82
	ds_read_b128 v[220:223], v202 offset:16384
	ds_read_b128 v[224:227], v202 offset:24576
	s_waitcnt lgkmcnt(10)
	v_mfma_f32_32x32x16_bf16 v[32:47], v[232:235], v[228:231], v[32:47]
	s_waitcnt lgkmcnt(9)
	v_mfma_f32_32x32x16_bf16 v[48:63], v[236:239], v[228:231], v[48:63]
	v_add_u32_e32 v203, v126, v141
	ds_read_b128 v[228:231], v83
	ds_read_b128 v[232:235], v203 offset:16384
	ds_read_b128 v[236:239], v203 offset:24576
	s_waitcnt lgkmcnt(10)
	v_mfma_f32_32x32x16_bf16 v[32:47], v[72:75], v[240:243], v[32:47]
	s_waitcnt lgkmcnt(9)
	v_mfma_f32_32x32x16_bf16 v[48:63], v[86:89], v[240:243], v[48:63]
	v_add_u32_e32 v244, v126, v142
	ds_read_b128 v[240:243], v84
	ds_read_b128 v[72:75], v244 offset:16384
	ds_read_b128 v[86:89], v244 offset:24576
	s_waitcnt lgkmcnt(10)
	v_mfma_f32_32x32x16_bf16 v[32:47], v[208:211], v[204:207], v[32:47]
	s_waitcnt lgkmcnt(9)
	v_mfma_f32_32x32x16_bf16 v[48:63], v[212:215], v[204:207], v[48:63]
	s_waitcnt lgkmcnt(7)
	v_mfma_f32_32x32x16_bf16 v[32:47], v[220:223], v[216:219], v[32:47]
	s_waitcnt lgkmcnt(6)
	v_mfma_f32_32x32x16_bf16 v[48:63], v[224:227], v[216:219], v[48:63]
	s_waitcnt lgkmcnt(4)
	v_mfma_f32_32x32x16_bf16 v[32:47], v[232:235], v[228:231], v[32:47]
	s_waitcnt lgkmcnt(3)
	v_mfma_f32_32x32x16_bf16 v[48:63], v[236:239], v[228:231], v[48:63]
	s_waitcnt lgkmcnt(1)
	v_mfma_f32_32x32x16_bf16 v[32:47], v[72:75], v[240:243], v[32:47]
	s_waitcnt lgkmcnt(0)
	v_mfma_f32_32x32x16_bf16 v[48:63], v[86:89], v[240:243], v[48:63]
	s_branch .LBB0_359
.Lscan_qk_tb0:
	v_add_u32_e32 v85, v126, v135
	ds_read_b128 v[204:207], v76
	ds_read_b128 v[208:211], v85 offset:16384
	v_add_u32_e32 v202, v126, v136
	ds_read_b128 v[216:219], v78
	ds_read_b128 v[220:223], v202 offset:16384
	v_add_u32_e32 v203, v126, v137
	ds_read_b128 v[228:231], v79
	ds_read_b128 v[232:235], v203 offset:16384
	v_add_u32_e32 v244, v126, v138
	ds_read_b128 v[240:243], v80
	ds_read_b128 v[72:75], v244 offset:16384
	s_waitcnt lgkmcnt(6)
	v_mfma_f32_32x32x16_bf16 v[32:47], v[208:211], v[204:207], 0
	v_add_u32_e32 v85, v126, v139
	ds_read_b128 v[204:207], v81
	ds_read_b128 v[208:211], v85 offset:16384
	s_waitcnt lgkmcnt(6)
	v_mfma_f32_32x32x16_bf16 v[32:47], v[220:223], v[216:219], v[32:47]
	v_add_u32_e32 v202, v126, v140
	ds_read_b128 v[216:219], v82
	ds_read_b128 v[220:223], v202 offset:16384
	s_waitcnt lgkmcnt(6)
	v_mfma_f32_32x32x16_bf16 v[32:47], v[232:235], v[228:231], v[32:47]
	v_add_u32_e32 v203, v126, v141
	ds_read_b128 v[228:231], v83
	ds_read_b128 v[232:235], v203 offset:16384
	s_waitcnt lgkmcnt(6)
	v_mfma_f32_32x32x16_bf16 v[32:47], v[72:75], v[240:243], v[32:47]
	v_add_u32_e32 v244, v126, v142
	ds_read_b128 v[240:243], v84
	ds_read_b128 v[72:75], v244 offset:16384
	s_waitcnt lgkmcnt(6)
	v_mfma_f32_32x32x16_bf16 v[32:47], v[208:211], v[204:207], v[32:47]
	s_waitcnt lgkmcnt(4)
	v_mfma_f32_32x32x16_bf16 v[32:47], v[220:223], v[216:219], v[32:47]
	s_waitcnt lgkmcnt(2)
	v_mfma_f32_32x32x16_bf16 v[32:47], v[232:235], v[228:231], v[32:47]
	s_waitcnt lgkmcnt(0)
	v_mfma_f32_32x32x16_bf16 v[32:47], v[72:75], v[240:243], v[32:47]
